# v37 + S5 C*x MFMA operand ds_reads hoisted (4 reads upfront, counted waits) at 8 sites
# speedup vs baseline: 1.0071x; 1.0071x over previous
.LBB0_689:
	v_sub_u32_e32 v44, 0x8ff, v26
	s_or_b64 exec, exec, s[6:7]
	s_add_i32 s2, s2, 4
	s_and_saveexec_b64 s[6:7], s[0:1]
	s_xor_b64 s[6:7], exec, s[6:7]
	v_lshl_or_b32 v6, s2, 4, v97
	v_sub_u32_e32 v6, 0x8ff, v6
	s_or_saveexec_b64 s[6:7], s[6:7]
	v_add_u32_e32 v24, 64, v25
	s_xor_b64 exec, exec, s[6:7]
	v_add_u32_e32 v6, 64, v25
	s_or_b64 exec, exec, s[6:7]
	v_add_u32_e32 v6, v6, v99
	v_ashrrev_i32_e32 v7, 31, v6
	v_lshlrev_b64 v[6:7], 5, v[6:7]
	v_lshl_add_u64 v[6:7], v[64:65], 0, v[6:7]
	global_load_dwordx2 v[86:87], v[6:7], off
	s_waitcnt vmcnt(4)
	v_mfma_f32_16x16x16_bf16 v[28:31], v[70:71], v[42:43], 0
	v_add_u32_e32 v27, 0x800, v100
	v_mfma_f32_16x16x16_bf16 v[32:35], v[72:73], v[42:43], 0
	v_mfma_f32_16x16x16_bf16 v[54:57], v[74:75], v[42:43], 0
	s_nop 4
	ds_write_b128 v98, v[28:31]
	v_mfma_f32_16x16x16_bf16 v[58:61], v[76:77], v[42:43], 0
	ds_write_b128 v98, v[32:35] offset:64
	ds_write_b128 v98, v[54:57] offset:128
	s_nop 5
	ds_write_b128 v98, v[58:61] offset:192
	v_mfma_f32_16x16x16_bf16 v[90:93], v[78:79], v[42:43], 0
	v_mfma_f32_16x16x16_bf16 v[28:31], v[48:49], v[42:43], 0
	v_mfma_f32_16x16x16_bf16 v[32:35], v[50:51], v[42:43], 0
	s_nop 5
	ds_write_b128 v98, v[90:93] offset:256
	ds_write_b128 v98, v[28:31] offset:320
	ds_write_b128 v98, v[32:35] offset:384
	v_mfma_f32_16x16x16_bf16 v[28:31], v[52:53], v[42:43], 0
	s_nop 7
	ds_write_b128 v98, v[28:31] offset:448
	s_waitcnt lgkmcnt(0)
	ds_read2_b64 v[30:33], v100 offset1:66
	ds_read2_b64 v[54:57], v100 offset0:132 offset1:198
	ds_read2_b64 v[58:61], v27 offset0:8 offset1:74
	ds_read2_b64 v[90:93], v27 offset0:140 offset1:206
	v_add_u32_e32 v28, 0x1000, v100
	v_add_u32_e32 v29, 0x1800, v100
	s_waitcnt lgkmcnt(3)
	v_pk_fma_f32 v[6:7], v[68:69], v[84:85], v[30:31]
	ds_read2_b64 v[102:105], v28 offset0:16 offset1:82
	ds_read2_b64 v[106:109], v28 offset0:148 offset1:214
	v_pk_fma_f32 v[6:7], v[66:67], v[84:85], v[6:7] op_sel:[0,1,0] op_sel_hi:[1,0,1]
	ds_read2_b64 v[110:113], v29 offset0:24 offset1:90
	ds_read2_b64 v[114:117], v29 offset0:156 offset1:222
	v_pk_fma_f32 v[30:31], v[68:69], v[6:7], v[32:33]
	v_cvt_pk_bf16_f32 v34, v6, v7
	v_pk_fma_f32 v[6:7], v[66:67], v[6:7], v[30:31] op_sel:[0,1,0] op_sel_hi:[1,0,1]
	v_add_u32_e32 v30, 0x2000, v101
	s_waitcnt lgkmcnt(6)
	v_pk_fma_f32 v[32:33], v[68:69], v[6:7], v[54:55]
	v_cvt_pk_bf16_f32 v31, v6, v7
	v_pk_fma_f32 v[6:7], v[66:67], v[6:7], v[32:33] op_sel:[0,1,0] op_sel_hi:[1,0,1]
	ds_write2_b32 v30, v34, v31 offset0:64 offset1:132
	v_pk_fma_f32 v[32:33], v[68:69], v[6:7], v[56:57]
	v_cvt_pk_bf16_f32 v34, v6, v7
	v_pk_fma_f32 v[6:7], v[66:67], v[6:7], v[32:33] op_sel:[0,1,0] op_sel_hi:[1,0,1]
	v_add_u32_e32 v31, 0x2200, v101
	v_cvt_pk_bf16_f32 v32, v6, v7
	ds_write2_b32 v31, v34, v32 offset0:72 offset1:140
	s_waitcnt lgkmcnt(7)
	v_pk_fma_f32 v[32:33], v[68:69], v[6:7], v[58:59]
	s_nop 0
	v_pk_fma_f32 v[6:7], v[66:67], v[6:7], v[32:33] op_sel:[0,1,0] op_sel_hi:[1,0,1]
	s_nop 0
	v_pk_fma_f32 v[32:33], v[68:69], v[6:7], v[60:61]
	v_cvt_pk_bf16_f32 v34, v6, v7
	v_pk_fma_f32 v[6:7], v[66:67], v[6:7], v[32:33] op_sel:[0,1,0] op_sel_hi:[1,0,1]
	v_add_u32_e32 v32, 0x2400, v101
	v_cvt_pk_bf16_f32 v33, v6, v7
	ds_write2_b32 v32, v34, v33 offset0:80 offset1:148
	s_waitcnt lgkmcnt(7)
	v_pk_fma_f32 v[34:35], v[68:69], v[6:7], v[90:91]
	v_add_u32_e32 v33, 0x2600, v101
	v_pk_fma_f32 v[6:7], v[66:67], v[6:7], v[34:35] op_sel:[0,1,0] op_sel_hi:[1,0,1]
	s_nop 0
	v_pk_fma_f32 v[34:35], v[68:69], v[6:7], v[92:93]
	v_cvt_pk_bf16_f32 v42, v6, v7
	v_pk_fma_f32 v[6:7], v[66:67], v[6:7], v[34:35] op_sel:[0,1,0] op_sel_hi:[1,0,1]
	s_nop 0
	v_cvt_pk_bf16_f32 v34, v6, v7
	ds_write2_b32 v33, v42, v34 offset0:88 offset1:156
	s_waitcnt lgkmcnt(7)
	v_pk_fma_f32 v[34:35], v[68:69], v[6:7], v[102:103]
	s_nop 0
	v_pk_fma_f32 v[6:7], v[66:67], v[6:7], v[34:35] op_sel:[0,1,0] op_sel_hi:[1,0,1]
	s_nop 0
	v_pk_fma_f32 v[34:35], v[68:69], v[6:7], v[104:105]
	v_cvt_pk_bf16_f32 v42, v6, v7
	v_pk_fma_f32 v[6:7], v[66:67], v[6:7], v[34:35] op_sel:[0,1,0] op_sel_hi:[1,0,1]
	v_add_u32_e32 v34, 0x2800, v101
	v_cvt_pk_bf16_f32 v35, v6, v7
	ds_write2_b32 v34, v42, v35 offset0:96 offset1:164
	s_waitcnt lgkmcnt(7)
	v_pk_fma_f32 v[42:43], v[68:69], v[6:7], v[106:107]
	v_add_u32_e32 v35, 0x2a00, v101
	v_pk_fma_f32 v[6:7], v[66:67], v[6:7], v[42:43] op_sel:[0,1,0] op_sel_hi:[1,0,1]
	s_nop 0
	v_pk_fma_f32 v[42:43], v[68:69], v[6:7], v[108:109]
	v_cvt_pk_bf16_f32 v45, v6, v7
	v_pk_fma_f32 v[6:7], v[66:67], v[6:7], v[42:43] op_sel:[0,1,0] op_sel_hi:[1,0,1]
	s_nop 0
	v_cvt_pk_bf16_f32 v42, v6, v7
	ds_write2_b32 v35, v45, v42 offset0:104 offset1:172
	s_waitcnt lgkmcnt(7)
	v_pk_fma_f32 v[42:43], v[68:69], v[6:7], v[110:111]
	s_nop 0
	v_pk_fma_f32 v[6:7], v[66:67], v[6:7], v[42:43] op_sel:[0,1,0] op_sel_hi:[1,0,1]
	s_nop 0
	v_pk_fma_f32 v[42:43], v[68:69], v[6:7], v[112:113]
	v_cvt_pk_bf16_f32 v45, v6, v7
	v_pk_fma_f32 v[6:7], v[66:67], v[6:7], v[42:43] op_sel:[0,1,0] op_sel_hi:[1,0,1]
	v_add_u32_e32 v42, 0x2c00, v101
	s_waitcnt lgkmcnt(6)
	v_pk_fma_f32 v[46:47], v[68:69], v[6:7], v[114:115]
	v_cvt_pk_bf16_f32 v43, v6, v7
	v_pk_fma_f32 v[6:7], v[66:67], v[6:7], v[46:47] op_sel:[0,1,0] op_sel_hi:[1,0,1]
	ds_write2_b32 v42, v45, v43 offset0:112 offset1:180
	v_pk_fma_f32 v[46:47], v[68:69], v[6:7], v[116:117]
	v_cvt_pk_bf16_f32 v45, v6, v7
	v_pk_fma_f32 v[6:7], v[66:67], v[6:7], v[46:47] op_sel:[0,1,0] op_sel_hi:[1,0,1]
	v_add_u32_e32 v43, 0x2e00, v101
	v_cvt_pk_bf16_f32 v46, v6, v7
	ds_write2_b32 v43, v45, v46 offset0:120 offset1:188
	s_waitcnt lgkmcnt(0)
	ds_read_b128 v[54:57], v88 offset:8448
	ds_read_b128 v[58:61], v88 offset:8512
	ds_read_b128 v[200:203], v88 offset:8576
	ds_read_b128 v[204:207], v88 offset:8640
	s_waitcnt lgkmcnt(3)
	v_mfma_f32_16x16x32_bf16 v[54:57], v[8:11], v[54:57], 0
	s_waitcnt lgkmcnt(2)
	v_mfma_f32_16x16x32_bf16 v[54:57], v[12:15], v[58:61], v[54:57]
	s_waitcnt lgkmcnt(1)
	v_mfma_f32_16x16x32_bf16 v[54:57], v[16:19], v[200:203], v[54:57]
	v_add_u32_e32 v58, v44, v99
	v_ashrrev_i32_e32 v59, 31, v58
	s_waitcnt lgkmcnt(0)
	v_mfma_f32_16x16x32_bf16 v[44:47], v[20:23], v[204:207], v[54:57]
	s_nop 3
	v_lshlrev_b64 v[54:55], 12, v[58:59]
	v_lshl_add_u64 v[54:55], v[4:5], 0, v[54:55]
	s_nop 1
	global_store_dwordx4 v[54:55], v[44:47], off
	s_and_saveexec_b64 s[6:7], s[0:1]
	s_xor_b64 s[6:7], exec, s[6:7]
	s_cbranch_execz .LBB0_696
	v_sub_u32_e32 v44, 0x8ef, v26
	s_andn2_saveexec_b64 s[6:7], s[6:7]
	s_branch .LBB0_697

.LBB0_702:
	s_or_b64 exec, exec, s[6:7]
	v_add_u32_e32 v46, v45, v99
	v_ashrrev_i32_e32 v47, 31, v46
	v_lshlrev_b64 v[46:47], 5, v[46:47]
	v_lshl_add_u64 v[46:47], v[64:65], 0, v[46:47]
	global_load_dwordx2 v[60:61], v[46:47], off
	s_waitcnt vmcnt(5)
	v_mfma_f32_16x16x16_bf16 v[54:57], v[70:71], v[40:41], 0
	v_mfma_f32_16x16x16_bf16 v[90:93], v[72:73], v[40:41], 0
	v_mfma_f32_16x16x16_bf16 v[102:105], v[74:75], v[40:41], 0
	s_nop 5
	ds_write_b128 v98, v[54:57]
	v_mfma_f32_16x16x16_bf16 v[106:109], v[76:77], v[40:41], 0
	ds_write_b128 v98, v[90:93] offset:64
	ds_write_b128 v98, v[102:105] offset:128
	s_nop 5
	ds_write_b128 v98, v[106:109] offset:192
	v_mfma_f32_16x16x16_bf16 v[110:113], v[78:79], v[40:41], 0
	v_mfma_f32_16x16x16_bf16 v[54:57], v[48:49], v[40:41], 0
	v_mfma_f32_16x16x16_bf16 v[90:93], v[50:51], v[40:41], 0
	s_nop 5
	ds_write_b128 v98, v[110:113] offset:256
	ds_write_b128 v98, v[54:57] offset:320
	ds_write_b128 v98, v[90:93] offset:384
	v_mfma_f32_16x16x16_bf16 v[54:57], v[52:53], v[40:41], 0
	s_nop 7
	ds_write_b128 v98, v[54:57] offset:448
	s_waitcnt lgkmcnt(0)
	ds_read2_b64 v[54:57], v100 offset1:66
	ds_read2_b64 v[90:93], v100 offset0:132 offset1:198
	ds_read2_b64 v[102:105], v27 offset0:8 offset1:74
	ds_read2_b64 v[106:109], v27 offset0:140 offset1:206
	ds_read2_b64 v[110:113], v28 offset0:16 offset1:82
	ds_read2_b64 v[114:117], v28 offset0:148 offset1:214
	ds_read2_b64 v[118:121], v29 offset0:24 offset1:90
	ds_read2_b64 v[122:125], v29 offset0:156 offset1:222
	s_waitcnt lgkmcnt(7)
	v_pk_fma_f32 v[40:41], v[68:69], v[6:7], v[54:55]
	s_nop 0
	v_pk_fma_f32 v[6:7], v[66:67], v[6:7], v[40:41] op_sel:[0,1,0] op_sel_hi:[1,0,1]
	s_nop 0
	v_pk_fma_f32 v[40:41], v[68:69], v[6:7], v[56:57]
	v_cvt_pk_bf16_f32 v45, v6, v7
	v_pk_fma_f32 v[6:7], v[66:67], v[6:7], v[40:41] op_sel:[0,1,0] op_sel_hi:[1,0,1]
	s_nop 0
	v_cvt_pk_bf16_f32 v40, v6, v7
	ds_write2_b32 v30, v45, v40 offset0:64 offset1:132
	s_waitcnt lgkmcnt(7)
	v_pk_fma_f32 v[40:41], v[68:69], v[6:7], v[90:91]
	s_nop 0
	v_pk_fma_f32 v[6:7], v[66:67], v[6:7], v[40:41] op_sel:[0,1,0] op_sel_hi:[1,0,1]
	s_nop 0
	v_pk_fma_f32 v[40:41], v[68:69], v[6:7], v[92:93]
	v_cvt_pk_bf16_f32 v45, v6, v7
	v_pk_fma_f32 v[6:7], v[66:67], v[6:7], v[40:41] op_sel:[0,1,0] op_sel_hi:[1,0,1]
	s_nop 0
	v_cvt_pk_bf16_f32 v40, v6, v7
	ds_write2_b32 v31, v45, v40 offset0:72 offset1:140
	s_waitcnt lgkmcnt(7)
	v_pk_fma_f32 v[40:41], v[68:69], v[6:7], v[102:103]
	s_nop 0
	v_pk_fma_f32 v[6:7], v[66:67], v[6:7], v[40:41] op_sel:[0,1,0] op_sel_hi:[1,0,1]
	s_nop 0
	v_pk_fma_f32 v[40:41], v[68:69], v[6:7], v[104:105]
	v_cvt_pk_bf16_f32 v45, v6, v7
	v_pk_fma_f32 v[6:7], v[66:67], v[6:7], v[40:41] op_sel:[0,1,0] op_sel_hi:[1,0,1]
	s_nop 0
	v_cvt_pk_bf16_f32 v40, v6, v7
	ds_write2_b32 v32, v45, v40 offset0:80 offset1:148
	s_waitcnt lgkmcnt(7)
	v_pk_fma_f32 v[40:41], v[68:69], v[6:7], v[106:107]
	s_nop 0
	v_pk_fma_f32 v[6:7], v[66:67], v[6:7], v[40:41] op_sel:[0,1,0] op_sel_hi:[1,0,1]
	s_nop 0
	v_pk_fma_f32 v[40:41], v[68:69], v[6:7], v[108:109]
	v_cvt_pk_bf16_f32 v45, v6, v7
	v_pk_fma_f32 v[6:7], v[66:67], v[6:7], v[40:41] op_sel:[0,1,0] op_sel_hi:[1,0,1]
	s_nop 0
	v_cvt_pk_bf16_f32 v40, v6, v7
	ds_write2_b32 v33, v45, v40 offset0:88 offset1:156
	s_waitcnt lgkmcnt(7)
	v_pk_fma_f32 v[40:41], v[68:69], v[6:7], v[110:111]
	s_nop 0
	v_pk_fma_f32 v[6:7], v[66:67], v[6:7], v[40:41] op_sel:[0,1,0] op_sel_hi:[1,0,1]
	s_nop 0
	v_pk_fma_f32 v[40:41], v[68:69], v[6:7], v[112:113]
	v_cvt_pk_bf16_f32 v45, v6, v7
	v_pk_fma_f32 v[6:7], v[66:67], v[6:7], v[40:41] op_sel:[0,1,0] op_sel_hi:[1,0,1]
	s_nop 0
	v_cvt_pk_bf16_f32 v40, v6, v7
	ds_write2_b32 v34, v45, v40 offset0:96 offset1:164
	s_waitcnt lgkmcnt(7)
	v_pk_fma_f32 v[40:41], v[68:69], v[6:7], v[114:115]
	s_nop 0
	v_pk_fma_f32 v[6:7], v[66:67], v[6:7], v[40:41] op_sel:[0,1,0] op_sel_hi:[1,0,1]
	s_nop 0
	v_pk_fma_f32 v[40:41], v[68:69], v[6:7], v[116:117]
	v_cvt_pk_bf16_f32 v45, v6, v7
	v_pk_fma_f32 v[6:7], v[66:67], v[6:7], v[40:41] op_sel:[0,1,0] op_sel_hi:[1,0,1]
	s_nop 0
	v_cvt_pk_bf16_f32 v40, v6, v7
	ds_write2_b32 v35, v45, v40 offset0:104 offset1:172
	s_waitcnt lgkmcnt(7)
	v_pk_fma_f32 v[40:41], v[68:69], v[6:7], v[118:119]
	s_nop 0
	v_pk_fma_f32 v[6:7], v[66:67], v[6:7], v[40:41] op_sel:[0,1,0] op_sel_hi:[1,0,1]
	s_nop 0
	v_pk_fma_f32 v[40:41], v[68:69], v[6:7], v[120:121]
	v_cvt_pk_bf16_f32 v45, v6, v7
	v_pk_fma_f32 v[6:7], v[66:67], v[6:7], v[40:41] op_sel:[0,1,0] op_sel_hi:[1,0,1]
	s_nop 0
	v_cvt_pk_bf16_f32 v40, v6, v7
	ds_write2_b32 v42, v45, v40 offset0:112 offset1:180
	s_waitcnt lgkmcnt(7)
	v_pk_fma_f32 v[40:41], v[68:69], v[6:7], v[122:123]
	s_nop 0
	v_pk_fma_f32 v[6:7], v[66:67], v[6:7], v[40:41] op_sel:[0,1,0] op_sel_hi:[1,0,1]
	s_nop 0
	v_pk_fma_f32 v[40:41], v[68:69], v[6:7], v[124:125]
	v_cvt_pk_bf16_f32 v45, v6, v7
	v_pk_fma_f32 v[6:7], v[66:67], v[6:7], v[40:41] op_sel:[0,1,0] op_sel_hi:[1,0,1]
	s_nop 0
	v_cvt_pk_bf16_f32 v40, v6, v7
	ds_write2_b32 v43, v45, v40 offset0:120 offset1:188
	s_waitcnt lgkmcnt(0)
	ds_read_b128 v[54:57], v88 offset:8448
	ds_read_b128 v[90:93], v88 offset:8512
	ds_read_b128 v[200:203], v88 offset:8576
	ds_read_b128 v[204:207], v88 offset:8640
	s_waitcnt lgkmcnt(3)
	v_mfma_f32_16x16x32_bf16 v[54:57], v[8:11], v[54:57], 0
	v_add_u32_e32 v40, v44, v99
	v_ashrrev_i32_e32 v41, 31, v40
	v_lshlrev_b64 v[40:41], 12, v[40:41]
	s_waitcnt lgkmcnt(2)
	v_mfma_f32_16x16x32_bf16 v[54:57], v[12:15], v[90:93], v[54:57]
	v_lshl_add_u64 v[40:41], v[4:5], 0, v[40:41]
	s_waitcnt lgkmcnt(1)
	v_mfma_f32_16x16x32_bf16 v[54:57], v[16:19], v[200:203], v[54:57]
	s_waitcnt lgkmcnt(0)
	v_mfma_f32_16x16x32_bf16 v[44:47], v[20:23], v[204:207], v[54:57]
	s_nop 7
	global_store_dwordx4 v[40:41], v[44:47], off
	s_and_saveexec_b64 s[6:7], s[0:1]
	s_xor_b64 s[6:7], exec, s[6:7]
	s_cbranch_execz .LBB0_704
	v_sub_u32_e32 v40, 0x8df, v26
	s_andn2_saveexec_b64 s[6:7], s[6:7]
	s_branch .LBB0_705

.LBB0_710:
	s_or_b64 exec, exec, s[6:7]
	v_add_u32_e32 v54, v41, v99
	v_ashrrev_i32_e32 v55, 31, v54
	v_lshlrev_b64 v[54:55], 5, v[54:55]
	v_lshl_add_u64 v[54:55], v[64:65], 0, v[54:55]
	global_load_dwordx2 v[56:57], v[54:55], off
	s_waitcnt vmcnt(6)
	v_mfma_f32_16x16x16_bf16 v[44:47], v[70:71], v[38:39], 0
	v_add_u32_e32 v54, v40, v99
	v_ashrrev_i32_e32 v55, 31, v54
	v_mfma_f32_16x16x16_bf16 v[90:93], v[72:73], v[38:39], 0
	v_mfma_f32_16x16x16_bf16 v[102:105], v[74:75], v[38:39], 0
	s_nop 3
	ds_write_b128 v98, v[44:47]
	v_mfma_f32_16x16x16_bf16 v[106:109], v[76:77], v[38:39], 0
	s_nop 0
	ds_write_b128 v98, v[90:93] offset:64
	ds_write_b128 v98, v[102:105] offset:128
	s_nop 4
	ds_write_b128 v98, v[106:109] offset:192
	v_mfma_f32_16x16x16_bf16 v[110:113], v[78:79], v[38:39], 0
	v_mfma_f32_16x16x16_bf16 v[44:47], v[48:49], v[38:39], 0
	v_mfma_f32_16x16x16_bf16 v[90:93], v[50:51], v[38:39], 0
	s_nop 5
	ds_write_b128 v98, v[110:113] offset:256
	ds_write_b128 v98, v[44:47] offset:320
	ds_write_b128 v98, v[90:93] offset:384
	v_mfma_f32_16x16x16_bf16 v[44:47], v[52:53], v[38:39], 0
	s_nop 7
	ds_write_b128 v98, v[44:47] offset:448
	s_waitcnt lgkmcnt(0)
	ds_read2_b64 v[44:47], v100 offset1:66
	ds_read2_b64 v[90:93], v100 offset0:132 offset1:198
	ds_read2_b64 v[102:105], v27 offset0:8 offset1:74
	ds_read2_b64 v[106:109], v27 offset0:140 offset1:206
	ds_read2_b64 v[110:113], v28 offset0:16 offset1:82
	ds_read2_b64 v[114:117], v28 offset0:148 offset1:214
	ds_read2_b64 v[118:121], v29 offset0:24 offset1:90
	ds_read2_b64 v[122:125], v29 offset0:156 offset1:222
	s_waitcnt lgkmcnt(7)
	v_pk_fma_f32 v[38:39], v[68:69], v[6:7], v[44:45]
	s_nop 0
	v_pk_fma_f32 v[6:7], v[66:67], v[6:7], v[38:39] op_sel:[0,1,0] op_sel_hi:[1,0,1]
	s_nop 0
	v_pk_fma_f32 v[38:39], v[68:69], v[6:7], v[46:47]
	v_cvt_pk_bf16_f32 v41, v6, v7
	v_pk_fma_f32 v[6:7], v[66:67], v[6:7], v[38:39] op_sel:[0,1,0] op_sel_hi:[1,0,1]
	s_nop 0
	v_cvt_pk_bf16_f32 v38, v6, v7
	ds_write2_b32 v30, v41, v38 offset0:64 offset1:132
	s_waitcnt lgkmcnt(7)
	v_pk_fma_f32 v[38:39], v[68:69], v[6:7], v[90:91]
	s_nop 0
	v_pk_fma_f32 v[6:7], v[66:67], v[6:7], v[38:39] op_sel:[0,1,0] op_sel_hi:[1,0,1]
	s_nop 0
	v_pk_fma_f32 v[38:39], v[68:69], v[6:7], v[92:93]
	v_cvt_pk_bf16_f32 v41, v6, v7
	v_pk_fma_f32 v[6:7], v[66:67], v[6:7], v[38:39] op_sel:[0,1,0] op_sel_hi:[1,0,1]
	s_nop 0
	v_cvt_pk_bf16_f32 v38, v6, v7
	ds_write2_b32 v31, v41, v38 offset0:72 offset1:140
	s_waitcnt lgkmcnt(7)
	v_pk_fma_f32 v[38:39], v[68:69], v[6:7], v[102:103]
	s_nop 0
	v_pk_fma_f32 v[6:7], v[66:67], v[6:7], v[38:39] op_sel:[0,1,0] op_sel_hi:[1,0,1]
	s_nop 0
	v_pk_fma_f32 v[38:39], v[68:69], v[6:7], v[104:105]
	v_cvt_pk_bf16_f32 v41, v6, v7
	v_pk_fma_f32 v[6:7], v[66:67], v[6:7], v[38:39] op_sel:[0,1,0] op_sel_hi:[1,0,1]
	s_nop 0
	v_cvt_pk_bf16_f32 v38, v6, v7
	ds_write2_b32 v32, v41, v38 offset0:80 offset1:148
	s_waitcnt lgkmcnt(7)
	v_pk_fma_f32 v[38:39], v[68:69], v[6:7], v[106:107]
	s_nop 0
	v_pk_fma_f32 v[6:7], v[66:67], v[6:7], v[38:39] op_sel:[0,1,0] op_sel_hi:[1,0,1]
	s_nop 0
	v_pk_fma_f32 v[38:39], v[68:69], v[6:7], v[108:109]
	v_cvt_pk_bf16_f32 v41, v6, v7
	v_pk_fma_f32 v[6:7], v[66:67], v[6:7], v[38:39] op_sel:[0,1,0] op_sel_hi:[1,0,1]
	s_nop 0
	v_cvt_pk_bf16_f32 v38, v6, v7
	ds_write2_b32 v33, v41, v38 offset0:88 offset1:156
	s_waitcnt lgkmcnt(7)
	v_pk_fma_f32 v[38:39], v[68:69], v[6:7], v[110:111]
	s_nop 0
	v_pk_fma_f32 v[6:7], v[66:67], v[6:7], v[38:39] op_sel:[0,1,0] op_sel_hi:[1,0,1]
	s_nop 0
	v_pk_fma_f32 v[38:39], v[68:69], v[6:7], v[112:113]
	v_cvt_pk_bf16_f32 v41, v6, v7
	v_pk_fma_f32 v[6:7], v[66:67], v[6:7], v[38:39] op_sel:[0,1,0] op_sel_hi:[1,0,1]
	s_nop 0
	v_cvt_pk_bf16_f32 v38, v6, v7
	ds_write2_b32 v34, v41, v38 offset0:96 offset1:164
	s_waitcnt lgkmcnt(7)
	v_pk_fma_f32 v[38:39], v[68:69], v[6:7], v[114:115]
	s_nop 0
	v_pk_fma_f32 v[6:7], v[66:67], v[6:7], v[38:39] op_sel:[0,1,0] op_sel_hi:[1,0,1]
	s_nop 0
	v_pk_fma_f32 v[38:39], v[68:69], v[6:7], v[116:117]
	v_cvt_pk_bf16_f32 v41, v6, v7
	v_pk_fma_f32 v[6:7], v[66:67], v[6:7], v[38:39] op_sel:[0,1,0] op_sel_hi:[1,0,1]
	s_nop 0
	v_cvt_pk_bf16_f32 v38, v6, v7
	ds_write2_b32 v35, v41, v38 offset0:104 offset1:172
	s_waitcnt lgkmcnt(7)
	v_pk_fma_f32 v[38:39], v[68:69], v[6:7], v[118:119]
	s_nop 0
	v_pk_fma_f32 v[6:7], v[66:67], v[6:7], v[38:39] op_sel:[0,1,0] op_sel_hi:[1,0,1]
	s_nop 0
	v_pk_fma_f32 v[38:39], v[68:69], v[6:7], v[120:121]
	v_cvt_pk_bf16_f32 v41, v6, v7
	v_pk_fma_f32 v[6:7], v[66:67], v[6:7], v[38:39] op_sel:[0,1,0] op_sel_hi:[1,0,1]
	s_nop 0
	v_cvt_pk_bf16_f32 v38, v6, v7
	ds_write2_b32 v42, v41, v38 offset0:112 offset1:180
	s_waitcnt lgkmcnt(7)
	v_pk_fma_f32 v[38:39], v[68:69], v[6:7], v[122:123]
	s_nop 0
	v_pk_fma_f32 v[6:7], v[66:67], v[6:7], v[38:39] op_sel:[0,1,0] op_sel_hi:[1,0,1]
	s_nop 0
	v_pk_fma_f32 v[38:39], v[68:69], v[6:7], v[124:125]
	v_cvt_pk_bf16_f32 v41, v6, v7
	v_pk_fma_f32 v[6:7], v[66:67], v[6:7], v[38:39] op_sel:[0,1,0] op_sel_hi:[1,0,1]
	s_nop 0
	v_cvt_pk_bf16_f32 v38, v6, v7
	ds_write2_b32 v43, v41, v38 offset0:120 offset1:188
	s_waitcnt lgkmcnt(0)
	ds_read_b128 v[44:47], v88 offset:8448
	ds_read_b128 v[90:93], v88 offset:8512
	ds_read_b128 v[200:203], v88 offset:8576
	ds_read_b128 v[204:207], v88 offset:8640
	s_waitcnt lgkmcnt(3)
	v_mfma_f32_16x16x32_bf16 v[44:47], v[8:11], v[44:47], 0
	s_waitcnt lgkmcnt(2)
	v_mfma_f32_16x16x32_bf16 v[44:47], v[12:15], v[90:93], v[44:47]
	s_waitcnt lgkmcnt(1)
	v_mfma_f32_16x16x32_bf16 v[44:47], v[16:19], v[200:203], v[44:47]
	s_waitcnt lgkmcnt(0)
	v_mfma_f32_16x16x32_bf16 v[38:41], v[20:23], v[204:207], v[44:47]
	s_nop 5
	v_lshlrev_b64 v[44:45], 12, v[54:55]
	v_lshl_add_u64 v[44:45], v[4:5], 0, v[44:45]
	global_store_dwordx4 v[44:45], v[38:41], off
	s_and_saveexec_b64 s[6:7], s[0:1]
	s_xor_b64 s[6:7], exec, s[6:7]
	s_cbranch_execz .LBB0_712
	v_sub_u32_e32 v38, 0x8cf, v26
	s_andn2_saveexec_b64 s[6:7], s[6:7]
	s_branch .LBB0_713

.LBB0_718:
	s_or_b64 exec, exec, s[6:7]
	v_add_u32_e32 v40, v39, v99
	v_ashrrev_i32_e32 v41, 31, v40
	v_lshlrev_b64 v[40:41], 5, v[40:41]
	v_lshl_add_u64 v[40:41], v[64:65], 0, v[40:41]
	global_load_dwordx2 v[58:59], v[40:41], off
	s_waitcnt vmcnt(7)
	v_mfma_f32_16x16x16_bf16 v[44:47], v[70:71], v[36:37], 0
	s_add_i32 s10, s10, 4
	s_cmpk_gt_u32 s10, 0x4b
	v_mfma_f32_16x16x16_bf16 v[90:93], v[72:73], v[36:37], 0
	v_mfma_f32_16x16x16_bf16 v[102:105], v[74:75], v[36:37], 0
	s_nop 3
	ds_write_b128 v98, v[44:47]
	v_mfma_f32_16x16x16_bf16 v[106:109], v[76:77], v[36:37], 0
	s_nop 0
	ds_write_b128 v98, v[90:93] offset:64
	ds_write_b128 v98, v[102:105] offset:128
	s_nop 4
	ds_write_b128 v98, v[106:109] offset:192
	v_mfma_f32_16x16x16_bf16 v[110:113], v[78:79], v[36:37], 0
	v_mfma_f32_16x16x16_bf16 v[44:47], v[48:49], v[36:37], 0
	v_mfma_f32_16x16x16_bf16 v[90:93], v[50:51], v[36:37], 0
	s_nop 5
	ds_write_b128 v98, v[110:113] offset:256
	ds_write_b128 v98, v[44:47] offset:320
	ds_write_b128 v98, v[90:93] offset:384
	v_mfma_f32_16x16x16_bf16 v[44:47], v[52:53], v[36:37], 0
	s_nop 7
	ds_write_b128 v98, v[44:47] offset:448
	s_waitcnt lgkmcnt(0)
	ds_read2_b64 v[44:47], v100 offset1:66
	ds_read2_b64 v[90:93], v100 offset0:132 offset1:198
	ds_read2_b64 v[102:105], v27 offset0:8 offset1:74
	ds_read2_b64 v[106:109], v27 offset0:140 offset1:206
	ds_read2_b64 v[110:113], v28 offset0:16 offset1:82
	ds_read2_b64 v[114:117], v28 offset0:148 offset1:214
	ds_read2_b64 v[118:121], v29 offset0:24 offset1:90
	ds_read2_b64 v[26:29], v29 offset0:156 offset1:222
	s_waitcnt lgkmcnt(7)
	v_pk_fma_f32 v[36:37], v[68:69], v[6:7], v[44:45]
	s_nop 0
	v_pk_fma_f32 v[6:7], v[66:67], v[6:7], v[36:37] op_sel:[0,1,0] op_sel_hi:[1,0,1]
	s_nop 0
	v_pk_fma_f32 v[36:37], v[68:69], v[6:7], v[46:47]
	v_cvt_pk_bf16_f32 v25, v6, v7
	v_pk_fma_f32 v[6:7], v[66:67], v[6:7], v[36:37] op_sel:[0,1,0] op_sel_hi:[1,0,1]
	s_nop 0
	v_cvt_pk_bf16_f32 v36, v6, v7
	ds_write2_b32 v30, v25, v36 offset0:64 offset1:132
	s_waitcnt lgkmcnt(7)
	v_pk_fma_f32 v[36:37], v[68:69], v[6:7], v[90:91]
	s_nop 0
	v_pk_fma_f32 v[6:7], v[66:67], v[6:7], v[36:37] op_sel:[0,1,0] op_sel_hi:[1,0,1]
	s_nop 0
	v_pk_fma_f32 v[36:37], v[68:69], v[6:7], v[92:93]
	v_cvt_pk_bf16_f32 v25, v6, v7
	v_pk_fma_f32 v[6:7], v[66:67], v[6:7], v[36:37] op_sel:[0,1,0] op_sel_hi:[1,0,1]
	s_nop 0
	v_cvt_pk_bf16_f32 v30, v6, v7
	ds_write2_b32 v31, v25, v30 offset0:72 offset1:140
	s_waitcnt lgkmcnt(7)
	v_pk_fma_f32 v[30:31], v[68:69], v[6:7], v[102:103]
	s_nop 0
	v_pk_fma_f32 v[6:7], v[66:67], v[6:7], v[30:31] op_sel:[0,1,0] op_sel_hi:[1,0,1]
	s_nop 0
	v_pk_fma_f32 v[30:31], v[68:69], v[6:7], v[104:105]
	v_cvt_pk_bf16_f32 v25, v6, v7
	v_pk_fma_f32 v[6:7], v[66:67], v[6:7], v[30:31] op_sel:[0,1,0] op_sel_hi:[1,0,1]
	s_nop 0
	v_cvt_pk_bf16_f32 v30, v6, v7
	ds_write2_b32 v32, v25, v30 offset0:80 offset1:148
	s_waitcnt lgkmcnt(7)
	v_pk_fma_f32 v[30:31], v[68:69], v[6:7], v[106:107]
	s_nop 0
	v_pk_fma_f32 v[6:7], v[66:67], v[6:7], v[30:31] op_sel:[0,1,0] op_sel_hi:[1,0,1]
	s_nop 0
	v_pk_fma_f32 v[30:31], v[68:69], v[6:7], v[108:109]
	v_cvt_pk_bf16_f32 v25, v6, v7
	v_pk_fma_f32 v[6:7], v[66:67], v[6:7], v[30:31] op_sel:[0,1,0] op_sel_hi:[1,0,1]
	s_nop 0
	v_cvt_pk_bf16_f32 v30, v6, v7
	ds_write2_b32 v33, v25, v30 offset0:88 offset1:156
	s_waitcnt lgkmcnt(7)
	v_pk_fma_f32 v[30:31], v[68:69], v[6:7], v[110:111]
	s_nop 0
	v_pk_fma_f32 v[6:7], v[66:67], v[6:7], v[30:31] op_sel:[0,1,0] op_sel_hi:[1,0,1]
	s_nop 0
	v_pk_fma_f32 v[30:31], v[68:69], v[6:7], v[112:113]
	v_cvt_pk_bf16_f32 v25, v6, v7
	v_pk_fma_f32 v[6:7], v[66:67], v[6:7], v[30:31] op_sel:[0,1,0] op_sel_hi:[1,0,1]
	s_nop 0
	v_cvt_pk_bf16_f32 v30, v6, v7
	ds_write2_b32 v34, v25, v30 offset0:96 offset1:164
	s_waitcnt lgkmcnt(7)
	v_pk_fma_f32 v[30:31], v[68:69], v[6:7], v[114:115]
	s_nop 0
	v_pk_fma_f32 v[6:7], v[66:67], v[6:7], v[30:31] op_sel:[0,1,0] op_sel_hi:[1,0,1]
	s_nop 0
	v_pk_fma_f32 v[30:31], v[68:69], v[6:7], v[116:117]
	v_cvt_pk_bf16_f32 v25, v6, v7
	v_pk_fma_f32 v[6:7], v[66:67], v[6:7], v[30:31] op_sel:[0,1,0] op_sel_hi:[1,0,1]
	s_nop 0
	v_cvt_pk_bf16_f32 v30, v6, v7
	ds_write2_b32 v35, v25, v30 offset0:104 offset1:172
	s_waitcnt lgkmcnt(7)
	v_pk_fma_f32 v[30:31], v[68:69], v[6:7], v[118:119]
	s_nop 0
	v_pk_fma_f32 v[6:7], v[66:67], v[6:7], v[30:31] op_sel:[0,1,0] op_sel_hi:[1,0,1]
	s_nop 0
	v_pk_fma_f32 v[30:31], v[68:69], v[6:7], v[120:121]
	v_cvt_pk_bf16_f32 v25, v6, v7
	v_pk_fma_f32 v[6:7], v[66:67], v[6:7], v[30:31] op_sel:[0,1,0] op_sel_hi:[1,0,1]
	s_waitcnt lgkmcnt(6)
	v_pk_fma_f32 v[26:27], v[68:69], v[6:7], v[26:27]
	v_cvt_pk_bf16_f32 v30, v6, v7
	v_pk_fma_f32 v[6:7], v[66:67], v[6:7], v[26:27] op_sel:[0,1,0] op_sel_hi:[1,0,1]
	ds_write2_b32 v42, v25, v30 offset0:112 offset1:180
	v_pk_fma_f32 v[26:27], v[68:69], v[6:7], v[28:29]
	v_cvt_pk_bf16_f32 v25, v6, v7
	v_pk_fma_f32 v[84:85], v[66:67], v[6:7], v[26:27] op_sel:[0,1,0] op_sel_hi:[1,0,1]
	s_nop 0
	v_cvt_pk_bf16_f32 v6, v84, v85
	ds_write2_b32 v43, v25, v6 offset0:120 offset1:188
	s_waitcnt lgkmcnt(0)
	ds_read_b128 v[26:29], v88 offset:8448
	ds_read_b128 v[30:33], v88 offset:8512
	ds_read_b128 v[200:203], v88 offset:8576
	ds_read_b128 v[204:207], v88 offset:8640
	s_waitcnt lgkmcnt(3)
	v_mfma_f32_16x16x32_bf16 v[26:29], v[8:11], v[26:29], 0
	v_add_u32_e32 v6, v38, v99
	v_ashrrev_i32_e32 v7, 31, v6
	v_lshlrev_b64 v[6:7], 12, v[6:7]
	s_waitcnt lgkmcnt(2)
	v_mfma_f32_16x16x32_bf16 v[26:29], v[12:15], v[30:33], v[26:29]
	v_lshl_add_u64 v[6:7], v[4:5], 0, v[6:7]
	s_waitcnt lgkmcnt(1)
	v_mfma_f32_16x16x32_bf16 v[26:29], v[16:19], v[200:203], v[26:29]
	s_waitcnt lgkmcnt(0)
	v_mfma_f32_16x16x32_bf16 v[26:29], v[20:23], v[204:207], v[26:29]
	s_nop 7
	global_store_dwordx4 v[6:7], v[26:29], off
	s_cbranch_scc0 .LBB0_688
	v_xor_b32_e32 v6, 0x3ff, v97
	v_or_b32_e32 v89, 0x400, v97
	v_cndmask_b32_e64 v6, v6, v89, s[8:9]
	v_xor_b32_e32 v24, 0x3ef, v97
	v_or_b32_e32 v25, 0x410, v97
	v_or_b32_e32 v6, v6, v99
	v_cndmask_b32_e64 v24, v24, v25, s[8:9]
	v_ashrrev_i32_e32 v7, 31, v6
	v_or_b32_e32 v24, v24, v99
	v_lshlrev_b64 v[6:7], 12, v[6:7]
	v_ashrrev_i32_e32 v25, 31, v24
	v_lshl_add_u64 v[6:7], v[4:5], 0, v[6:7]
	v_lshlrev_b64 v[24:25], 12, v[24:25]
	s_barrier
	v_lshl_add_u64 v[24:25], v[4:5], 0, v[24:25]
	global_load_dwordx4 v[40:43], v[6:7], off
	global_load_dwordx4 v[36:39], v[24:25], off
	v_xor_b32_e32 v6, 0x3df, v97
	v_or_b32_e32 v7, 0x420, v97
	v_cndmask_b32_e64 v6, v6, v7, s[8:9]
	v_xor_b32_e32 v24, 0x3cf, v97
	v_or_b32_e32 v25, 0x430, v97
	v_or_b32_e32 v6, v6, v99
	v_cndmask_b32_e64 v24, v24, v25, s[8:9]
	v_ashrrev_i32_e32 v7, 31, v6
	v_or_b32_e32 v24, v24, v99
	v_lshlrev_b64 v[6:7], 12, v[6:7]
	v_ashrrev_i32_e32 v25, 31, v24
	v_lshl_add_u64 v[6:7], v[4:5], 0, v[6:7]
	v_lshlrev_b64 v[24:25], 12, v[24:25]
	v_lshl_add_u64 v[28:29], v[4:5], 0, v[24:25]
	global_load_dwordx4 v[32:35], v[6:7], off
	global_load_dwordx4 v[24:27], v[28:29], off
	v_lshlrev_b32_e32 v6, 1, v82
	v_mov_b32_e32 v7, 0
	v_lshl_add_u64 v[28:29], s[22:23], 0, v[6:7]
	v_lshlrev_b32_e32 v6, 1, v80
	v_lshl_add_u64 v[6:7], v[28:29], 0, v[6:7]
	s_mov_b64 s[6:7], 0x14a00000
	v_or_b32_e32 v90, 0xffffff00, v97
	v_lshl_add_u64 v[54:55], v[6:7], 0, s[6:7]
	s_movk_i32 s2, 0x50
	s_movk_i32 s10, 0x4c
	s_mov_b32 s8, 0xffff
	s_waitcnt vmcnt(5)
	v_mov_b32_e32 v6, v58
	v_mov_b32_e32 v7, v59
	s_branch .LBB0_721

.LBB0_721:
	v_lshl_or_b32 v103, s2, 4, v97
	v_mov_b32_e32 v80, v89
	s_and_saveexec_b64 s[6:7], s[0:1]
	v_sub_u32_e32 v80, 0x8ff, v103
	s_or_b64 exec, exec, s[6:7]
	s_add_i32 s9, s10, 4
	s_min_u32 s11, s9, 0x8b
	s_add_i32 s11, s11, 4
	v_lshl_or_b32 v29, s11, 4, v97
	s_and_saveexec_b64 s[6:7], s[0:1]
	s_xor_b64 s[6:7], exec, s[6:7]
	v_sub_u32_e32 v30, 0x8ff, v29
	s_or_saveexec_b64 s[6:7], s[6:7]
	v_lshl_add_u32 v28, s11, 4, v90
	s_xor_b64 exec, exec, s[6:7]
	v_lshl_add_u32 v30, s11, 4, v90
	s_or_b64 exec, exec, s[6:7]
	v_add_u32_e32 v30, v30, v99
	v_ashrrev_i32_e32 v31, 31, v30
	v_lshlrev_b64 v[30:31], 5, v[30:31]
	v_lshl_add_u64 v[30:31], v[64:65], 0, v[30:31]
	global_load_dwordx2 v[62:63], v[30:31], off
	v_mfma_f32_16x16x16_bf16 v[44:47], v[70:71], v[86:87], 0
	v_add_u32_e32 v91, 0x800, v100
	v_add_u32_e32 v102, 0x2400, v101
	v_mfma_f32_16x16x16_bf16 v[92:95], v[72:73], v[86:87], 0
	v_mfma_f32_16x16x16_bf16 v[104:107], v[74:75], v[86:87], 0
	s_nop 3
	ds_write_b128 v98, v[44:47]
	v_mfma_f32_16x16x16_bf16 v[108:111], v[76:77], v[86:87], 0
	s_nop 0
	ds_write_b128 v98, v[92:95] offset:64
	ds_write_b128 v98, v[104:107] offset:128
	s_nop 4
	ds_write_b128 v98, v[108:111] offset:192
	v_mfma_f32_16x16x16_bf16 v[112:115], v[78:79], v[86:87], 0
	v_mfma_f32_16x16x16_bf16 v[44:47], v[48:49], v[86:87], 0
	v_mfma_f32_16x16x16_bf16 v[92:95], v[50:51], v[86:87], 0
	s_nop 5
	ds_write_b128 v98, v[112:115] offset:256
	ds_write_b128 v98, v[44:47] offset:320
	ds_write_b128 v98, v[92:95] offset:384
	v_add_u32_e32 v92, 0x1000, v100
	v_mfma_f32_16x16x16_bf16 v[44:47], v[52:53], v[86:87], 0
	v_add_u32_e32 v93, 0x1800, v100
	v_add_u32_e32 v94, 0x2000, v101
	v_add_u32_e32 v95, 0x2200, v101
	s_nop 4
	ds_write_b128 v98, v[44:47] offset:448
	s_waitcnt lgkmcnt(0)
	ds_read2_b64 v[44:47], v100 offset1:66
	ds_read2_b64 v[104:107], v100 offset0:132 offset1:198
	ds_read2_b64 v[108:111], v91 offset0:8 offset1:74
	ds_read2_b64 v[112:115], v91 offset0:140 offset1:206
	ds_read2_b64 v[116:119], v92 offset0:16 offset1:82
	ds_read2_b64 v[120:123], v92 offset0:148 offset1:214
	ds_read2_b64 v[124:127], v93 offset0:24 offset1:90
	ds_read2_b64 v[128:131], v93 offset0:156 offset1:222
	s_waitcnt lgkmcnt(7)
	v_pk_fma_f32 v[30:31], v[68:69], v[84:85], v[44:45]
	s_nop 0
	v_pk_fma_f32 v[30:31], v[66:67], v[84:85], v[30:31] op_sel:[0,1,0] op_sel_hi:[1,0,1]
	s_nop 0
	v_pk_fma_f32 v[44:45], v[68:69], v[30:31], v[46:47]
	v_cvt_pk_bf16_f32 v81, v30, v31
	v_pk_fma_f32 v[30:31], v[66:67], v[30:31], v[44:45] op_sel:[0,1,0] op_sel_hi:[1,0,1]
	s_nop 0
	v_cvt_pk_bf16_f32 v44, v30, v31
	ds_write2_b32 v94, v81, v44 offset0:64 offset1:132
	s_waitcnt lgkmcnt(7)
	v_pk_fma_f32 v[44:45], v[68:69], v[30:31], v[104:105]
	v_add_u32_e32 v104, 0x2600, v101
	v_pk_fma_f32 v[30:31], v[66:67], v[30:31], v[44:45] op_sel:[0,1,0] op_sel_hi:[1,0,1]
	v_add_u32_e32 v105, 0x2800, v101
	v_pk_fma_f32 v[44:45], v[68:69], v[30:31], v[106:107]
	v_cvt_pk_bf16_f32 v46, v30, v31
	v_pk_fma_f32 v[30:31], v[66:67], v[30:31], v[44:45] op_sel:[0,1,0] op_sel_hi:[1,0,1]
	v_add_u32_e32 v106, 0x2a00, v101
	v_cvt_pk_bf16_f32 v44, v30, v31
	ds_write2_b32 v95, v46, v44 offset0:72 offset1:140
	s_waitcnt lgkmcnt(7)
	v_pk_fma_f32 v[44:45], v[68:69], v[30:31], v[108:109]
	v_add_u32_e32 v107, 0x2c00, v101
	v_pk_fma_f32 v[30:31], v[66:67], v[30:31], v[44:45] op_sel:[0,1,0] op_sel_hi:[1,0,1]
	v_add_u32_e32 v108, 0x2e00, v101
	v_pk_fma_f32 v[44:45], v[68:69], v[30:31], v[110:111]
	v_cvt_pk_bf16_f32 v46, v30, v31
	v_pk_fma_f32 v[30:31], v[66:67], v[30:31], v[44:45] op_sel:[0,1,0] op_sel_hi:[1,0,1]
	s_nop 0
	v_cvt_pk_bf16_f32 v44, v30, v31
	ds_write2_b32 v102, v46, v44 offset0:80 offset1:148
	s_waitcnt lgkmcnt(7)
	v_pk_fma_f32 v[44:45], v[68:69], v[30:31], v[112:113]
	s_nop 0
	v_pk_fma_f32 v[30:31], v[66:67], v[30:31], v[44:45] op_sel:[0,1,0] op_sel_hi:[1,0,1]
	s_nop 0
	v_pk_fma_f32 v[44:45], v[68:69], v[30:31], v[114:115]
	v_cvt_pk_bf16_f32 v46, v30, v31
	v_pk_fma_f32 v[30:31], v[66:67], v[30:31], v[44:45] op_sel:[0,1,0] op_sel_hi:[1,0,1]
	s_nop 0
	v_cvt_pk_bf16_f32 v44, v30, v31
	ds_write2_b32 v104, v46, v44 offset0:88 offset1:156
	s_waitcnt lgkmcnt(7)
	v_pk_fma_f32 v[44:45], v[68:69], v[30:31], v[116:117]
	s_nop 0
	v_pk_fma_f32 v[30:31], v[66:67], v[30:31], v[44:45] op_sel:[0,1,0] op_sel_hi:[1,0,1]
	s_nop 0
	v_pk_fma_f32 v[44:45], v[68:69], v[30:31], v[118:119]
	v_cvt_pk_bf16_f32 v46, v30, v31
	v_pk_fma_f32 v[30:31], v[66:67], v[30:31], v[44:45] op_sel:[0,1,0] op_sel_hi:[1,0,1]
	s_nop 0
	v_cvt_pk_bf16_f32 v44, v30, v31
	ds_write2_b32 v105, v46, v44 offset0:96 offset1:164
	s_waitcnt lgkmcnt(7)
	v_pk_fma_f32 v[44:45], v[68:69], v[30:31], v[120:121]
	s_nop 0
	v_pk_fma_f32 v[30:31], v[66:67], v[30:31], v[44:45] op_sel:[0,1,0] op_sel_hi:[1,0,1]
	s_nop 0
	v_pk_fma_f32 v[44:45], v[68:69], v[30:31], v[122:123]
	v_cvt_pk_bf16_f32 v46, v30, v31
	v_pk_fma_f32 v[30:31], v[66:67], v[30:31], v[44:45] op_sel:[0,1,0] op_sel_hi:[1,0,1]
	s_nop 0
	v_cvt_pk_bf16_f32 v44, v30, v31
	ds_write2_b32 v106, v46, v44 offset0:104 offset1:172
	s_waitcnt lgkmcnt(7)
	v_pk_fma_f32 v[44:45], v[68:69], v[30:31], v[124:125]
	s_nop 0
	v_pk_fma_f32 v[30:31], v[66:67], v[30:31], v[44:45] op_sel:[0,1,0] op_sel_hi:[1,0,1]
	s_nop 0
	v_pk_fma_f32 v[44:45], v[68:69], v[30:31], v[126:127]
	v_cvt_pk_bf16_f32 v46, v30, v31
	v_pk_fma_f32 v[30:31], v[66:67], v[30:31], v[44:45] op_sel:[0,1,0] op_sel_hi:[1,0,1]
	s_nop 0
	v_cvt_pk_bf16_f32 v44, v30, v31
	ds_write2_b32 v107, v46, v44 offset0:112 offset1:180
	s_waitcnt lgkmcnt(7)
	v_pk_fma_f32 v[44:45], v[68:69], v[30:31], v[128:129]
	s_nop 0
	v_pk_fma_f32 v[30:31], v[66:67], v[30:31], v[44:45] op_sel:[0,1,0] op_sel_hi:[1,0,1]
	s_nop 0
	v_pk_fma_f32 v[44:45], v[68:69], v[30:31], v[130:131]
	v_cvt_pk_bf16_f32 v46, v30, v31
	v_pk_fma_f32 v[82:83], v[66:67], v[30:31], v[44:45] op_sel:[0,1,0] op_sel_hi:[1,0,1]
	s_nop 0
	v_cvt_pk_bf16_f32 v30, v82, v83
	ds_write2_b32 v108, v46, v30 offset0:120 offset1:188
	s_waitcnt lgkmcnt(0)
	ds_read_b128 v[44:47], v88 offset:8448
	ds_read_b128 v[110:113], v88 offset:8512
	ds_read_b128 v[200:203], v88 offset:8576
	ds_read_b128 v[204:207], v88 offset:8640
	s_waitcnt lgkmcnt(3)
	v_mfma_f32_16x16x32_bf16 v[44:47], v[8:11], v[44:47], 0
	s_waitcnt lgkmcnt(2)
	v_mfma_f32_16x16x32_bf16 v[44:47], v[12:15], v[110:113], v[44:47]
	s_waitcnt lgkmcnt(1)
	v_mfma_f32_16x16x32_bf16 v[44:47], v[16:19], v[200:203], v[44:47]
	s_waitcnt lgkmcnt(0)
	v_mfma_f32_16x16x32_bf16 v[44:47], v[20:23], v[204:207], v[44:47]
	s_and_saveexec_b64 s[6:7], s[0:1]
	s_xor_b64 s[6:7], exec, s[6:7]
	v_sub_u32_e32 v28, 0x8ff, v29
	s_andn2_saveexec_b64 s[6:7], s[6:7]
	s_or_b64 exec, exec, s[6:7]
	v_add_u32_e32 v28, v28, v99
	v_ashrrev_i32_e32 v29, 31, v28
	v_lshlrev_b64 v[28:29], 12, v[28:29]
	v_lshl_add_u64 v[28:29], v[4:5], 0, v[28:29]
	global_load_dwordx4 v[28:31], v[28:29], off
	v_lshlrev_b32_e32 v84, 16, v86
	v_and_b32_e32 v85, 0xffff0000, v86
	s_waitcnt vmcnt(5)
	v_pk_add_f32 v[40:41], v[40:41], v[44:45]
	v_lshlrev_b32_e32 v86, 16, v87
	v_and_b32_e32 v87, 0xffff0000, v87
	v_pk_fma_f32 v[40:41], v[0:1], v[84:85], v[40:41]
	v_pk_add_f32 v[42:43], v[42:43], v[46:47]
	v_mul_f32_e32 v44, 0x3d372713, v40
	v_mul_f32_e32 v45, 0x3d372713, v41
	v_pk_fma_f32 v[42:43], v[2:3], v[86:87], v[42:43]
	v_mul_f32_e32 v44, v40, v44
	v_mul_f32_e32 v45, v41, v45
	v_mul_f32_e32 v46, 0x3d372713, v42
	v_mul_f32_e32 v47, 0x3d372713, v43
	v_fma_f32 v44, v40, v44, v40
	v_fma_f32 v45, v41, v45, v41
	v_mul_f32_e32 v46, v42, v46
	v_mul_f32_e32 v47, v43, v47
	v_mul_f32_e32 v44, 0x3f4c422a, v44
	v_mul_f32_e32 v45, 0x3f4c422a, v45
	v_fma_f32 v46, v42, v46, v42
	v_fma_f32 v47, v43, v47, v43
	v_mul_f32_e32 v44, 0x4038aa3b, v44
	v_mul_f32_e32 v45, 0x4038aa3b, v45
	v_mul_f32_e32 v46, 0x3f4c422a, v46
	v_mul_f32_e32 v47, 0x3f4c422a, v47
	v_exp_f32_e32 v44, v44
	v_exp_f32_e32 v45, v45
	v_mul_f32_e32 v46, 0x4038aa3b, v46
	v_mul_f32_e32 v47, 0x4038aa3b, v47
	v_exp_f32_e32 v46, v46
	v_exp_f32_e32 v47, v47
	v_add_f32_e32 v44, 1.0, v44
	v_add_f32_e32 v45, 1.0, v45
	v_rcp_f32_e32 v44, v44
	v_rcp_f32_e32 v45, v45
	v_add_f32_e32 v46, 1.0, v46
	v_add_f32_e32 v47, 1.0, v47
	v_rcp_f32_e32 v46, v46
	v_rcp_f32_e32 v47, v47
	v_pk_add_f32 v[44:45], v[44:45], 1.0 op_sel_hi:[1,0] neg_lo:[1,0] neg_hi:[1,0]
	v_add_u32_e32 v80, v80, v99
	v_pk_mul_f32 v[40:41], v[40:41], v[44:45]
	v_pk_add_f32 v[44:45], v[46:47], 1.0 op_sel_hi:[1,0] neg_lo:[1,0] neg_hi:[1,0]
	v_ashrrev_i32_e32 v81, 31, v80
	v_pk_mul_f32 v[42:43], v[42:43], v[44:45]
	v_cvt_pk_bf16_f32 v40, v40, v41
	v_cvt_pk_bf16_f32 v41, v42, v43
	v_lshlrev_b64 v[42:43], 11, v[80:81]
	v_lshl_add_u64 v[42:43], v[54:55], 0, v[42:43]
	global_store_dwordx2 v[42:43], v[40:41], off
	s_and_saveexec_b64 s[6:7], s[0:1]
	s_xor_b64 s[6:7], exec, s[6:7]
	v_sub_u32_e32 v86, 0x8ef, v103
	s_andn2_saveexec_b64 s[6:7], s[6:7]
	v_add_u32_e32 v86, 16, v89
	s_or_b64 exec, exec, s[6:7]
	s_add_i32 s6, s10, 5
	s_min_u32 s11, s6, 0x8b
	s_add_i32 s11, s11, 4
	v_lshl_or_b32 v41, s11, 4, v97
	s_and_saveexec_b64 s[6:7], s[0:1]
	s_xor_b64 s[6:7], exec, s[6:7]
	v_sub_u32_e32 v42, 0x8ff, v41
	s_or_saveexec_b64 s[6:7], s[6:7]
	v_lshl_add_u32 v40, s11, 4, v90
	s_xor_b64 exec, exec, s[6:7]
	v_lshl_add_u32 v42, s11, 4, v90
	s_or_b64 exec, exec, s[6:7]
	v_add_u32_e32 v42, v42, v99
	v_ashrrev_i32_e32 v43, 31, v42
	v_lshlrev_b64 v[42:43], 5, v[42:43]
	v_lshl_add_u64 v[42:43], v[64:65], 0, v[42:43]
	global_load_dwordx2 v[80:81], v[42:43], off
	v_mfma_f32_16x16x16_bf16 v[44:47], v[70:71], v[60:61], 0
	v_mfma_f32_16x16x16_bf16 v[110:113], v[72:73], v[60:61], 0
	v_mfma_f32_16x16x16_bf16 v[114:117], v[74:75], v[60:61], 0
	s_nop 5
	ds_write_b128 v98, v[44:47]
	v_mfma_f32_16x16x16_bf16 v[118:121], v[76:77], v[60:61], 0
	ds_write_b128 v98, v[110:113] offset:64
	ds_write_b128 v98, v[114:117] offset:128
	s_nop 5
	ds_write_b128 v98, v[118:121] offset:192
	v_mfma_f32_16x16x16_bf16 v[122:125], v[78:79], v[60:61], 0
	v_mfma_f32_16x16x16_bf16 v[42:45], v[48:49], v[60:61], 0
	v_mfma_f32_16x16x16_bf16 v[110:113], v[50:51], v[60:61], 0
	s_nop 5
	ds_write_b128 v98, v[122:125] offset:256
	ds_write_b128 v98, v[42:45] offset:320
	ds_write_b128 v98, v[110:113] offset:384
	v_mfma_f32_16x16x16_bf16 v[42:45], v[52:53], v[60:61], 0
	s_nop 7
	ds_write_b128 v98, v[42:45] offset:448
	s_waitcnt lgkmcnt(0)
	ds_read2_b64 v[42:45], v100 offset1:66
	ds_read2_b64 v[110:113], v100 offset0:132 offset1:198
	ds_read2_b64 v[114:117], v91 offset0:8 offset1:74
	ds_read2_b64 v[118:121], v91 offset0:140 offset1:206
	ds_read2_b64 v[122:125], v92 offset0:16 offset1:82
	ds_read2_b64 v[126:129], v92 offset0:148 offset1:214
	ds_read2_b64 v[130:133], v93 offset0:24 offset1:90
	ds_read2_b64 v[134:137], v93 offset0:156 offset1:222
	s_waitcnt lgkmcnt(7)
	v_pk_fma_f32 v[42:43], v[68:69], v[82:83], v[42:43]
	s_nop 0
	v_pk_fma_f32 v[42:43], v[66:67], v[82:83], v[42:43] op_sel:[0,1,0] op_sel_hi:[1,0,1]
	s_nop 0
	v_pk_fma_f32 v[44:45], v[68:69], v[42:43], v[44:45]
	v_cvt_pk_bf16_f32 v46, v42, v43
	v_pk_fma_f32 v[42:43], v[66:67], v[42:43], v[44:45] op_sel:[0,1,0] op_sel_hi:[1,0,1]
	s_nop 0
	v_cvt_pk_bf16_f32 v44, v42, v43
	ds_write2_b32 v94, v46, v44 offset0:64 offset1:132
	s_waitcnt lgkmcnt(7)
	v_pk_fma_f32 v[44:45], v[68:69], v[42:43], v[110:111]
	s_nop 0
	v_pk_fma_f32 v[42:43], v[66:67], v[42:43], v[44:45] op_sel:[0,1,0] op_sel_hi:[1,0,1]
	s_nop 0
	v_pk_fma_f32 v[44:45], v[68:69], v[42:43], v[112:113]
	v_cvt_pk_bf16_f32 v46, v42, v43
	v_pk_fma_f32 v[42:43], v[66:67], v[42:43], v[44:45] op_sel:[0,1,0] op_sel_hi:[1,0,1]
	s_nop 0
	v_cvt_pk_bf16_f32 v44, v42, v43
	ds_write2_b32 v95, v46, v44 offset0:72 offset1:140
	s_waitcnt lgkmcnt(7)
	v_pk_fma_f32 v[44:45], v[68:69], v[42:43], v[114:115]
	s_nop 0
	v_pk_fma_f32 v[42:43], v[66:67], v[42:43], v[44:45] op_sel:[0,1,0] op_sel_hi:[1,0,1]
	s_nop 0
	v_pk_fma_f32 v[44:45], v[68:69], v[42:43], v[116:117]
	v_cvt_pk_bf16_f32 v46, v42, v43
	v_pk_fma_f32 v[42:43], v[66:67], v[42:43], v[44:45] op_sel:[0,1,0] op_sel_hi:[1,0,1]
	s_nop 0
	v_cvt_pk_bf16_f32 v44, v42, v43
	ds_write2_b32 v102, v46, v44 offset0:80 offset1:148
	s_waitcnt lgkmcnt(7)
	v_pk_fma_f32 v[44:45], v[68:69], v[42:43], v[118:119]
	s_nop 0
	v_pk_fma_f32 v[42:43], v[66:67], v[42:43], v[44:45] op_sel:[0,1,0] op_sel_hi:[1,0,1]
	s_nop 0
	v_pk_fma_f32 v[44:45], v[68:69], v[42:43], v[120:121]
	v_cvt_pk_bf16_f32 v46, v42, v43
	v_pk_fma_f32 v[42:43], v[66:67], v[42:43], v[44:45] op_sel:[0,1,0] op_sel_hi:[1,0,1]
	s_nop 0
	v_cvt_pk_bf16_f32 v44, v42, v43
	ds_write2_b32 v104, v46, v44 offset0:88 offset1:156
	s_waitcnt lgkmcnt(7)
	v_pk_fma_f32 v[44:45], v[68:69], v[42:43], v[122:123]
	s_nop 0
	v_pk_fma_f32 v[42:43], v[66:67], v[42:43], v[44:45] op_sel:[0,1,0] op_sel_hi:[1,0,1]
	s_nop 0
	v_pk_fma_f32 v[44:45], v[68:69], v[42:43], v[124:125]
	v_cvt_pk_bf16_f32 v46, v42, v43
	v_pk_fma_f32 v[42:43], v[66:67], v[42:43], v[44:45] op_sel:[0,1,0] op_sel_hi:[1,0,1]
	s_nop 0
	v_cvt_pk_bf16_f32 v44, v42, v43
	ds_write2_b32 v105, v46, v44 offset0:96 offset1:164
	s_waitcnt lgkmcnt(7)
	v_pk_fma_f32 v[44:45], v[68:69], v[42:43], v[126:127]
	s_nop 0
	v_pk_fma_f32 v[42:43], v[66:67], v[42:43], v[44:45] op_sel:[0,1,0] op_sel_hi:[1,0,1]
	s_nop 0
	v_pk_fma_f32 v[44:45], v[68:69], v[42:43], v[128:129]
	v_cvt_pk_bf16_f32 v46, v42, v43
	v_pk_fma_f32 v[42:43], v[66:67], v[42:43], v[44:45] op_sel:[0,1,0] op_sel_hi:[1,0,1]
	s_nop 0
	v_cvt_pk_bf16_f32 v44, v42, v43
	ds_write2_b32 v106, v46, v44 offset0:104 offset1:172
	s_waitcnt lgkmcnt(7)
	v_pk_fma_f32 v[44:45], v[68:69], v[42:43], v[130:131]
	s_nop 0
	v_pk_fma_f32 v[42:43], v[66:67], v[42:43], v[44:45] op_sel:[0,1,0] op_sel_hi:[1,0,1]
	s_nop 0
	v_pk_fma_f32 v[44:45], v[68:69], v[42:43], v[132:133]
	v_cvt_pk_bf16_f32 v46, v42, v43
	v_pk_fma_f32 v[42:43], v[66:67], v[42:43], v[44:45] op_sel:[0,1,0] op_sel_hi:[1,0,1]
	s_nop 0
	v_cvt_pk_bf16_f32 v44, v42, v43
	ds_write2_b32 v107, v46, v44 offset0:112 offset1:180
	s_waitcnt lgkmcnt(7)
	v_pk_fma_f32 v[44:45], v[68:69], v[42:43], v[134:135]
	s_nop 0
	v_pk_fma_f32 v[42:43], v[66:67], v[42:43], v[44:45] op_sel:[0,1,0] op_sel_hi:[1,0,1]
	s_nop 0
	v_pk_fma_f32 v[44:45], v[68:69], v[42:43], v[136:137]
	v_cvt_pk_bf16_f32 v46, v42, v43
	v_pk_fma_f32 v[84:85], v[66:67], v[42:43], v[44:45] op_sel:[0,1,0] op_sel_hi:[1,0,1]
	s_nop 0
	v_cvt_pk_bf16_f32 v42, v84, v85
	ds_write2_b32 v108, v46, v42 offset0:120 offset1:188
	s_waitcnt lgkmcnt(0)
	ds_read_b128 v[42:45], v88 offset:8448
	ds_read_b128 v[110:113], v88 offset:8512
	ds_read_b128 v[200:203], v88 offset:8576
	ds_read_b128 v[204:207], v88 offset:8640
	s_waitcnt lgkmcnt(3)
	v_mfma_f32_16x16x32_bf16 v[42:45], v[8:11], v[42:45], 0
	s_waitcnt lgkmcnt(2)
	v_mfma_f32_16x16x32_bf16 v[42:45], v[12:15], v[110:113], v[42:45]
	s_waitcnt lgkmcnt(1)
	v_mfma_f32_16x16x32_bf16 v[42:45], v[16:19], v[200:203], v[42:45]
	s_waitcnt lgkmcnt(0)
	v_mfma_f32_16x16x32_bf16 v[44:47], v[20:23], v[204:207], v[42:45]
	s_and_saveexec_b64 s[6:7], s[0:1]
	s_xor_b64 s[6:7], exec, s[6:7]
	v_sub_u32_e32 v40, 0x8ff, v41
	s_andn2_saveexec_b64 s[6:7], s[6:7]
	s_or_b64 exec, exec, s[6:7]
	v_add_u32_e32 v40, v40, v99
	v_ashrrev_i32_e32 v41, 31, v40
	v_lshlrev_b64 v[40:41], 12, v[40:41]
	v_lshl_add_u64 v[40:41], v[4:5], 0, v[40:41]
	global_load_dwordx4 v[40:43], v[40:41], off
	v_add_u32_e32 v82, v86, v99
	v_lshlrev_b32_e32 v86, 16, v60
	v_and_b32_e32 v87, 0xffff0000, v60
	s_waitcnt vmcnt(7)
	v_pk_add_f32 v[36:37], v[36:37], v[44:45]
	v_lshlrev_b32_e32 v60, 16, v61
	v_and_b32_e32 v61, 0xffff0000, v61
	v_pk_fma_f32 v[36:37], v[0:1], v[86:87], v[36:37]
	v_pk_add_f32 v[38:39], v[38:39], v[46:47]
	v_mul_f32_e32 v44, 0x3d372713, v36
	v_mul_f32_e32 v45, 0x3d372713, v37
	v_pk_fma_f32 v[38:39], v[2:3], v[60:61], v[38:39]
	v_mul_f32_e32 v44, v36, v44
	v_mul_f32_e32 v45, v37, v45
	v_mul_f32_e32 v46, 0x3d372713, v38
	v_mul_f32_e32 v47, 0x3d372713, v39
	v_fma_f32 v44, v36, v44, v36
	v_fma_f32 v45, v37, v45, v37
	v_mul_f32_e32 v46, v38, v46
	v_mul_f32_e32 v47, v39, v47
	v_mul_f32_e32 v44, 0x3f4c422a, v44
	v_mul_f32_e32 v45, 0x3f4c422a, v45
	v_fma_f32 v46, v38, v46, v38
	v_fma_f32 v47, v39, v47, v39
	v_mul_f32_e32 v44, 0x4038aa3b, v44
	v_mul_f32_e32 v45, 0x4038aa3b, v45
	v_mul_f32_e32 v46, 0x3f4c422a, v46
	v_mul_f32_e32 v47, 0x3f4c422a, v47
	v_exp_f32_e32 v44, v44
	v_exp_f32_e32 v45, v45
	v_mul_f32_e32 v46, 0x4038aa3b, v46
	v_mul_f32_e32 v47, 0x4038aa3b, v47
	v_exp_f32_e32 v46, v46
	v_exp_f32_e32 v47, v47
	v_add_f32_e32 v44, 1.0, v44
	v_add_f32_e32 v45, 1.0, v45
	v_rcp_f32_e32 v44, v44
	v_rcp_f32_e32 v45, v45
	v_add_f32_e32 v46, 1.0, v46
	v_add_f32_e32 v47, 1.0, v47
	v_rcp_f32_e32 v46, v46
	v_rcp_f32_e32 v47, v47
	v_pk_add_f32 v[44:45], v[44:45], 1.0 op_sel_hi:[1,0] neg_lo:[1,0] neg_hi:[1,0]
	v_ashrrev_i32_e32 v83, 31, v82
	v_pk_mul_f32 v[36:37], v[36:37], v[44:45]
	v_pk_add_f32 v[44:45], v[46:47], 1.0 op_sel_hi:[1,0] neg_lo:[1,0] neg_hi:[1,0]
	v_cvt_pk_bf16_f32 v36, v36, v37
	v_pk_mul_f32 v[38:39], v[38:39], v[44:45]
	s_nop 0
	v_cvt_pk_bf16_f32 v37, v38, v39
	v_lshlrev_b64 v[38:39], 11, v[82:83]
	v_lshl_add_u64 v[38:39], v[54:55], 0, v[38:39]
	global_store_dwordx2 v[38:39], v[36:37], off
	s_and_saveexec_b64 s[6:7], s[0:1]
	s_xor_b64 s[6:7], exec, s[6:7]
	v_sub_u32_e32 v86, 0x8df, v103
	s_andn2_saveexec_b64 s[6:7], s[6:7]
	v_add_u32_e32 v86, 32, v89
	s_or_b64 exec, exec, s[6:7]
	s_add_i32 s6, s10, 6
	s_min_u32 s11, s6, 0x8b
	s_add_i32 s11, s11, 4
	v_lshl_or_b32 v37, s11, 4, v97
	s_and_saveexec_b64 s[6:7], s[0:1]
	s_xor_b64 s[6:7], exec, s[6:7]
	v_sub_u32_e32 v38, 0x8ff, v37
	s_or_saveexec_b64 s[6:7], s[6:7]
	v_lshl_add_u32 v36, s11, 4, v90
	s_xor_b64 exec, exec, s[6:7]
	v_lshl_add_u32 v38, s11, 4, v90
	s_or_b64 exec, exec, s[6:7]
	v_add_u32_e32 v38, v38, v99
	v_ashrrev_i32_e32 v39, 31, v38
	v_lshlrev_b64 v[38:39], 5, v[38:39]
	v_lshl_add_u64 v[38:39], v[64:65], 0, v[38:39]
	global_load_dwordx2 v[82:83], v[38:39], off
	v_mfma_f32_16x16x16_bf16 v[44:47], v[70:71], v[56:57], 0
	v_mfma_f32_16x16x16_bf16 v[110:113], v[72:73], v[56:57], 0
	v_mfma_f32_16x16x16_bf16 v[114:117], v[74:75], v[56:57], 0
	s_nop 5
	ds_write_b128 v98, v[44:47]
	v_mfma_f32_16x16x16_bf16 v[118:121], v[76:77], v[56:57], 0
	ds_write_b128 v98, v[110:113] offset:64
	ds_write_b128 v98, v[114:117] offset:128
	s_nop 5
	ds_write_b128 v98, v[118:121] offset:192
	v_mfma_f32_16x16x16_bf16 v[122:125], v[78:79], v[56:57], 0
	v_mfma_f32_16x16x16_bf16 v[44:47], v[48:49], v[56:57], 0
	v_mfma_f32_16x16x16_bf16 v[110:113], v[50:51], v[56:57], 0
	s_nop 5
	ds_write_b128 v98, v[122:125] offset:256
	ds_write_b128 v98, v[44:47] offset:320
	ds_write_b128 v98, v[110:113] offset:384
	v_mfma_f32_16x16x16_bf16 v[44:47], v[52:53], v[56:57], 0
	s_nop 7
	ds_write_b128 v98, v[44:47] offset:448
	s_waitcnt lgkmcnt(0)
	ds_read2_b64 v[44:47], v100 offset1:66
	ds_read2_b64 v[110:113], v100 offset0:132 offset1:198
	ds_read2_b64 v[114:117], v91 offset0:8 offset1:74
	ds_read2_b64 v[118:121], v91 offset0:140 offset1:206
	ds_read2_b64 v[122:125], v92 offset0:16 offset1:82
	ds_read2_b64 v[126:129], v92 offset0:148 offset1:214
	ds_read2_b64 v[130:133], v93 offset0:24 offset1:90
	ds_read2_b64 v[134:137], v93 offset0:156 offset1:222
	s_waitcnt lgkmcnt(7)
	v_pk_fma_f32 v[38:39], v[68:69], v[84:85], v[44:45]
	s_nop 0
	v_pk_fma_f32 v[38:39], v[66:67], v[84:85], v[38:39] op_sel:[0,1,0] op_sel_hi:[1,0,1]
	s_nop 0
	v_pk_fma_f32 v[44:45], v[68:69], v[38:39], v[46:47]
	v_cvt_pk_bf16_f32 v60, v38, v39
	v_pk_fma_f32 v[38:39], v[66:67], v[38:39], v[44:45] op_sel:[0,1,0] op_sel_hi:[1,0,1]
	s_nop 0
	v_cvt_pk_bf16_f32 v44, v38, v39
	ds_write2_b32 v94, v60, v44 offset0:64 offset1:132
	s_waitcnt lgkmcnt(7)
	v_pk_fma_f32 v[44:45], v[68:69], v[38:39], v[110:111]
	s_nop 0
	v_pk_fma_f32 v[38:39], v[66:67], v[38:39], v[44:45] op_sel:[0,1,0] op_sel_hi:[1,0,1]
	s_nop 0
	v_pk_fma_f32 v[44:45], v[68:69], v[38:39], v[112:113]
	v_cvt_pk_bf16_f32 v46, v38, v39
	v_pk_fma_f32 v[38:39], v[66:67], v[38:39], v[44:45] op_sel:[0,1,0] op_sel_hi:[1,0,1]
	s_nop 0
	v_cvt_pk_bf16_f32 v44, v38, v39
	ds_write2_b32 v95, v46, v44 offset0:72 offset1:140
	s_waitcnt lgkmcnt(7)
	v_pk_fma_f32 v[44:45], v[68:69], v[38:39], v[114:115]
	s_nop 0
	v_pk_fma_f32 v[38:39], v[66:67], v[38:39], v[44:45] op_sel:[0,1,0] op_sel_hi:[1,0,1]
	s_nop 0
	v_pk_fma_f32 v[44:45], v[68:69], v[38:39], v[116:117]
	v_cvt_pk_bf16_f32 v46, v38, v39
	v_pk_fma_f32 v[38:39], v[66:67], v[38:39], v[44:45] op_sel:[0,1,0] op_sel_hi:[1,0,1]
	s_nop 0
	v_cvt_pk_bf16_f32 v44, v38, v39
	ds_write2_b32 v102, v46, v44 offset0:80 offset1:148
	s_waitcnt lgkmcnt(7)
	v_pk_fma_f32 v[44:45], v[68:69], v[38:39], v[118:119]
	s_nop 0
	v_pk_fma_f32 v[38:39], v[66:67], v[38:39], v[44:45] op_sel:[0,1,0] op_sel_hi:[1,0,1]
	s_nop 0
	v_pk_fma_f32 v[44:45], v[68:69], v[38:39], v[120:121]
	v_cvt_pk_bf16_f32 v46, v38, v39
	v_pk_fma_f32 v[38:39], v[66:67], v[38:39], v[44:45] op_sel:[0,1,0] op_sel_hi:[1,0,1]
	s_nop 0
	v_cvt_pk_bf16_f32 v44, v38, v39
	ds_write2_b32 v104, v46, v44 offset0:88 offset1:156
	s_waitcnt lgkmcnt(7)
	v_pk_fma_f32 v[44:45], v[68:69], v[38:39], v[122:123]
	s_nop 0
	v_pk_fma_f32 v[38:39], v[66:67], v[38:39], v[44:45] op_sel:[0,1,0] op_sel_hi:[1,0,1]
	s_nop 0
	v_pk_fma_f32 v[44:45], v[68:69], v[38:39], v[124:125]
	v_cvt_pk_bf16_f32 v46, v38, v39
	v_pk_fma_f32 v[38:39], v[66:67], v[38:39], v[44:45] op_sel:[0,1,0] op_sel_hi:[1,0,1]
	s_nop 0
	v_cvt_pk_bf16_f32 v44, v38, v39
	ds_write2_b32 v105, v46, v44 offset0:96 offset1:164
	s_waitcnt lgkmcnt(7)
	v_pk_fma_f32 v[44:45], v[68:69], v[38:39], v[126:127]
	s_nop 0
	v_pk_fma_f32 v[38:39], v[66:67], v[38:39], v[44:45] op_sel:[0,1,0] op_sel_hi:[1,0,1]
	s_nop 0
	v_pk_fma_f32 v[44:45], v[68:69], v[38:39], v[128:129]
	v_cvt_pk_bf16_f32 v46, v38, v39
	v_pk_fma_f32 v[38:39], v[66:67], v[38:39], v[44:45] op_sel:[0,1,0] op_sel_hi:[1,0,1]
	s_nop 0
	v_cvt_pk_bf16_f32 v44, v38, v39
	ds_write2_b32 v106, v46, v44 offset0:104 offset1:172
	s_waitcnt lgkmcnt(7)
	v_pk_fma_f32 v[44:45], v[68:69], v[38:39], v[130:131]
	s_nop 0
	v_pk_fma_f32 v[38:39], v[66:67], v[38:39], v[44:45] op_sel:[0,1,0] op_sel_hi:[1,0,1]
	s_nop 0
	v_pk_fma_f32 v[44:45], v[68:69], v[38:39], v[132:133]
	v_cvt_pk_bf16_f32 v46, v38, v39
	v_pk_fma_f32 v[38:39], v[66:67], v[38:39], v[44:45] op_sel:[0,1,0] op_sel_hi:[1,0,1]
	s_nop 0
	v_cvt_pk_bf16_f32 v44, v38, v39
	ds_write2_b32 v107, v46, v44 offset0:112 offset1:180
	s_waitcnt lgkmcnt(7)
	v_pk_fma_f32 v[44:45], v[68:69], v[38:39], v[134:135]
	s_nop 0
	v_pk_fma_f32 v[38:39], v[66:67], v[38:39], v[44:45] op_sel:[0,1,0] op_sel_hi:[1,0,1]
	s_nop 0
	v_pk_fma_f32 v[44:45], v[68:69], v[38:39], v[136:137]
	v_cvt_pk_bf16_f32 v46, v38, v39
	v_pk_fma_f32 v[60:61], v[66:67], v[38:39], v[44:45] op_sel:[0,1,0] op_sel_hi:[1,0,1]
	s_nop 0
	v_cvt_pk_bf16_f32 v38, v60, v61
	ds_write2_b32 v108, v46, v38 offset0:120 offset1:188
	s_waitcnt lgkmcnt(0)
	ds_read_b128 v[44:47], v88 offset:8448
	ds_read_b128 v[110:113], v88 offset:8512
	ds_read_b128 v[200:203], v88 offset:8576
	ds_read_b128 v[204:207], v88 offset:8640
	s_waitcnt lgkmcnt(3)
	v_mfma_f32_16x16x32_bf16 v[44:47], v[8:11], v[44:47], 0
	s_waitcnt lgkmcnt(2)
	v_mfma_f32_16x16x32_bf16 v[44:47], v[12:15], v[110:113], v[44:47]
	s_waitcnt lgkmcnt(1)
	v_mfma_f32_16x16x32_bf16 v[44:47], v[16:19], v[200:203], v[44:47]
	s_waitcnt lgkmcnt(0)
	v_mfma_f32_16x16x32_bf16 v[44:47], v[20:23], v[204:207], v[44:47]
	s_and_saveexec_b64 s[6:7], s[0:1]
	s_xor_b64 s[6:7], exec, s[6:7]
	v_sub_u32_e32 v36, 0x8ff, v37
	s_andn2_saveexec_b64 s[6:7], s[6:7]
	s_or_b64 exec, exec, s[6:7]
	v_add_u32_e32 v36, v36, v99
	v_ashrrev_i32_e32 v37, 31, v36
	v_lshlrev_b64 v[36:37], 12, v[36:37]
	v_lshl_add_u64 v[36:37], v[4:5], 0, v[36:37]
	global_load_dwordx4 v[36:39], v[36:37], off
	v_add_u32_e32 v84, v86, v99
	v_lshlrev_b32_e32 v86, 16, v56
	v_and_b32_e32 v87, 0xffff0000, v56
	s_waitcnt vmcnt(9)
	v_pk_add_f32 v[32:33], v[32:33], v[44:45]
	v_lshlrev_b32_e32 v56, 16, v57
	v_and_b32_e32 v57, 0xffff0000, v57
	v_pk_fma_f32 v[32:33], v[0:1], v[86:87], v[32:33]
	v_pk_add_f32 v[34:35], v[34:35], v[46:47]
	v_mul_f32_e32 v44, 0x3d372713, v32
	v_mul_f32_e32 v45, 0x3d372713, v33
	v_pk_fma_f32 v[34:35], v[2:3], v[56:57], v[34:35]
	v_mul_f32_e32 v44, v32, v44
	v_mul_f32_e32 v45, v33, v45
	v_mul_f32_e32 v46, 0x3d372713, v34
	v_mul_f32_e32 v47, 0x3d372713, v35
	v_fma_f32 v44, v32, v44, v32
	v_fma_f32 v45, v33, v45, v33
	v_mul_f32_e32 v46, v34, v46
	v_mul_f32_e32 v47, v35, v47
	v_mul_f32_e32 v44, 0x3f4c422a, v44
	v_mul_f32_e32 v45, 0x3f4c422a, v45
	v_fma_f32 v46, v34, v46, v34
	v_fma_f32 v47, v35, v47, v35
	v_mul_f32_e32 v44, 0x4038aa3b, v44
	v_mul_f32_e32 v45, 0x4038aa3b, v45
	v_mul_f32_e32 v46, 0x3f4c422a, v46
	v_mul_f32_e32 v47, 0x3f4c422a, v47
	v_exp_f32_e32 v44, v44
	v_exp_f32_e32 v45, v45
	v_mul_f32_e32 v46, 0x4038aa3b, v46
	v_mul_f32_e32 v47, 0x4038aa3b, v47
	v_exp_f32_e32 v46, v46
	v_exp_f32_e32 v47, v47
	v_add_f32_e32 v44, 1.0, v44
	v_add_f32_e32 v45, 1.0, v45
	v_rcp_f32_e32 v44, v44
	v_rcp_f32_e32 v45, v45
	v_add_f32_e32 v46, 1.0, v46
	v_add_f32_e32 v47, 1.0, v47
	v_rcp_f32_e32 v46, v46
	v_rcp_f32_e32 v47, v47
	v_pk_add_f32 v[44:45], v[44:45], 1.0 op_sel_hi:[1,0] neg_lo:[1,0] neg_hi:[1,0]
	v_ashrrev_i32_e32 v85, 31, v84
	v_pk_mul_f32 v[32:33], v[32:33], v[44:45]
	v_pk_add_f32 v[44:45], v[46:47], 1.0 op_sel_hi:[1,0] neg_lo:[1,0] neg_hi:[1,0]
	v_cvt_pk_bf16_f32 v32, v32, v33
	v_pk_mul_f32 v[34:35], v[34:35], v[44:45]
	s_nop 0
	v_cvt_pk_bf16_f32 v33, v34, v35
	v_lshlrev_b64 v[34:35], 11, v[84:85]
	v_lshl_add_u64 v[34:35], v[54:55], 0, v[34:35]
	global_store_dwordx2 v[34:35], v[32:33], off
	s_and_saveexec_b64 s[6:7], s[0:1]
	s_xor_b64 s[6:7], exec, s[6:7]
	v_sub_u32_e32 v46, 0x8cf, v103
	s_andn2_saveexec_b64 s[6:7], s[6:7]
	v_add_u32_e32 v46, 48, v89
	s_or_b64 exec, exec, s[6:7]
	s_add_i32 s6, s10, 7
	s_min_u32 s10, s6, 0x8b
	s_add_i32 s10, s10, 4
	v_lshl_or_b32 v56, s10, 4, v97
	s_and_saveexec_b64 s[6:7], s[0:1]
	s_xor_b64 s[6:7], exec, s[6:7]
	v_sub_u32_e32 v32, 0x8ff, v56
	s_or_saveexec_b64 s[6:7], s[6:7]
	v_lshl_add_u32 v47, s10, 4, v90
	s_xor_b64 exec, exec, s[6:7]
	v_lshl_add_u32 v32, s10, 4, v90
	s_or_b64 exec, exec, s[6:7]
	v_add_u32_e32 v32, v32, v99
	v_ashrrev_i32_e32 v33, 31, v32
	v_lshlrev_b64 v[44:45], 5, v[32:33]
	v_lshl_add_u64 v[44:45], v[64:65], 0, v[44:45]
	global_load_dwordx2 v[44:45], v[44:45], off
	v_bfi_b32 v58, s8, v6, v58
	v_bfi_b32 v59, s8, v7, v59
	s_nop 1
	v_mfma_f32_16x16x16_bf16 v[84:87], v[70:71], v[58:59], 0
	v_mfma_f32_16x16x16_bf16 v[110:113], v[72:73], v[58:59], 0
	v_mfma_f32_16x16x16_bf16 v[114:117], v[74:75], v[58:59], 0
	s_nop 5
	ds_write_b128 v98, v[84:87]
	v_mfma_f32_16x16x16_bf16 v[118:121], v[76:77], v[58:59], 0
	ds_write_b128 v98, v[110:113] offset:64
	ds_write_b128 v98, v[114:117] offset:128
	s_nop 5
	ds_write_b128 v98, v[118:121] offset:192
	v_mfma_f32_16x16x16_bf16 v[32:35], v[78:79], v[58:59], 0
	v_mfma_f32_16x16x16_bf16 v[84:87], v[48:49], v[58:59], 0
	v_mfma_f32_16x16x16_bf16 v[110:113], v[50:51], v[58:59], 0
	s_nop 5
	ds_write_b128 v98, v[32:35] offset:256
	ds_write_b128 v98, v[84:87] offset:320
	ds_write_b128 v98, v[110:113] offset:384
	v_mfma_f32_16x16x16_bf16 v[32:35], v[52:53], v[58:59], 0
	s_nop 7
	ds_write_b128 v98, v[32:35] offset:448
	s_waitcnt lgkmcnt(0)
	ds_read2_b64 v[32:35], v100 offset1:66
	ds_read2_b64 v[84:87], v100 offset0:132 offset1:198
	ds_read2_b64 v[110:113], v91 offset0:8 offset1:74
	ds_read2_b64 v[114:117], v91 offset0:140 offset1:206
	ds_read2_b64 v[118:121], v92 offset0:16 offset1:82
	ds_read2_b64 v[122:125], v92 offset0:148 offset1:214
	ds_read2_b64 v[126:129], v93 offset0:24 offset1:90
	ds_read2_b64 v[130:133], v93 offset0:156 offset1:222
	s_waitcnt lgkmcnt(7)
	v_pk_fma_f32 v[32:33], v[68:69], v[60:61], v[32:33]
	s_nop 0
	v_pk_fma_f32 v[32:33], v[66:67], v[60:61], v[32:33] op_sel:[0,1,0] op_sel_hi:[1,0,1]
	s_nop 0
	v_pk_fma_f32 v[34:35], v[68:69], v[32:33], v[34:35]
	v_cvt_pk_bf16_f32 v57, v32, v33
	v_pk_fma_f32 v[32:33], v[66:67], v[32:33], v[34:35] op_sel:[0,1,0] op_sel_hi:[1,0,1]
	s_nop 0
	v_cvt_pk_bf16_f32 v34, v32, v33
	ds_write2_b32 v94, v57, v34 offset0:64 offset1:132
	s_waitcnt lgkmcnt(7)
	v_pk_fma_f32 v[34:35], v[68:69], v[32:33], v[84:85]
	s_nop 0
	v_pk_fma_f32 v[32:33], v[66:67], v[32:33], v[34:35] op_sel:[0,1,0] op_sel_hi:[1,0,1]
	s_nop 0
	v_pk_fma_f32 v[34:35], v[68:69], v[32:33], v[86:87]
	v_cvt_pk_bf16_f32 v57, v32, v33
	v_pk_fma_f32 v[32:33], v[66:67], v[32:33], v[34:35] op_sel:[0,1,0] op_sel_hi:[1,0,1]
	s_nop 0
	v_cvt_pk_bf16_f32 v34, v32, v33
	ds_write2_b32 v95, v57, v34 offset0:72 offset1:140
	s_waitcnt lgkmcnt(7)
	v_pk_fma_f32 v[34:35], v[68:69], v[32:33], v[110:111]
	s_nop 0
	v_pk_fma_f32 v[32:33], v[66:67], v[32:33], v[34:35] op_sel:[0,1,0] op_sel_hi:[1,0,1]
	s_nop 0
	v_pk_fma_f32 v[34:35], v[68:69], v[32:33], v[112:113]
	v_cvt_pk_bf16_f32 v57, v32, v33
	v_pk_fma_f32 v[32:33], v[66:67], v[32:33], v[34:35] op_sel:[0,1,0] op_sel_hi:[1,0,1]
	s_nop 0
	v_cvt_pk_bf16_f32 v34, v32, v33
	ds_write2_b32 v102, v57, v34 offset0:80 offset1:148
	s_waitcnt lgkmcnt(7)
	v_pk_fma_f32 v[34:35], v[68:69], v[32:33], v[114:115]
	s_nop 0
	v_pk_fma_f32 v[32:33], v[66:67], v[32:33], v[34:35] op_sel:[0,1,0] op_sel_hi:[1,0,1]
	s_nop 0
	v_pk_fma_f32 v[34:35], v[68:69], v[32:33], v[116:117]
	v_cvt_pk_bf16_f32 v57, v32, v33
	v_pk_fma_f32 v[32:33], v[66:67], v[32:33], v[34:35] op_sel:[0,1,0] op_sel_hi:[1,0,1]
	s_nop 0
	v_cvt_pk_bf16_f32 v34, v32, v33
	ds_write2_b32 v104, v57, v34 offset0:88 offset1:156
	s_waitcnt lgkmcnt(7)
	v_pk_fma_f32 v[34:35], v[68:69], v[32:33], v[118:119]
	s_nop 0
	v_pk_fma_f32 v[32:33], v[66:67], v[32:33], v[34:35] op_sel:[0,1,0] op_sel_hi:[1,0,1]
	s_nop 0
	v_pk_fma_f32 v[34:35], v[68:69], v[32:33], v[120:121]
	v_cvt_pk_bf16_f32 v57, v32, v33
	v_pk_fma_f32 v[32:33], v[66:67], v[32:33], v[34:35] op_sel:[0,1,0] op_sel_hi:[1,0,1]
	s_nop 0
	v_cvt_pk_bf16_f32 v34, v32, v33
	ds_write2_b32 v105, v57, v34 offset0:96 offset1:164
	s_waitcnt lgkmcnt(7)
	v_pk_fma_f32 v[34:35], v[68:69], v[32:33], v[122:123]
	s_nop 0
	v_pk_fma_f32 v[32:33], v[66:67], v[32:33], v[34:35] op_sel:[0,1,0] op_sel_hi:[1,0,1]
	s_nop 0
	v_pk_fma_f32 v[34:35], v[68:69], v[32:33], v[124:125]
	v_cvt_pk_bf16_f32 v57, v32, v33
	v_pk_fma_f32 v[32:33], v[66:67], v[32:33], v[34:35] op_sel:[0,1,0] op_sel_hi:[1,0,1]
	s_nop 0
	v_cvt_pk_bf16_f32 v34, v32, v33
	ds_write2_b32 v106, v57, v34 offset0:104 offset1:172
	s_waitcnt lgkmcnt(7)
	v_pk_fma_f32 v[34:35], v[68:69], v[32:33], v[126:127]
	s_nop 0
	v_pk_fma_f32 v[32:33], v[66:67], v[32:33], v[34:35] op_sel:[0,1,0] op_sel_hi:[1,0,1]
	s_nop 0
	v_pk_fma_f32 v[34:35], v[68:69], v[32:33], v[128:129]
	v_cvt_pk_bf16_f32 v57, v32, v33
	v_pk_fma_f32 v[32:33], v[66:67], v[32:33], v[34:35] op_sel:[0,1,0] op_sel_hi:[1,0,1]
	s_nop 0
	v_cvt_pk_bf16_f32 v34, v32, v33
	ds_write2_b32 v107, v57, v34 offset0:112 offset1:180
	s_waitcnt lgkmcnt(7)
	v_pk_fma_f32 v[34:35], v[68:69], v[32:33], v[130:131]
	s_nop 0
	v_pk_fma_f32 v[32:33], v[66:67], v[32:33], v[34:35] op_sel:[0,1,0] op_sel_hi:[1,0,1]
	s_nop 0
	v_pk_fma_f32 v[34:35], v[68:69], v[32:33], v[132:133]
	v_cvt_pk_bf16_f32 v57, v32, v33
	v_pk_fma_f32 v[84:85], v[66:67], v[32:33], v[34:35] op_sel:[0,1,0] op_sel_hi:[1,0,1]
	s_nop 0
	v_cvt_pk_bf16_f32 v32, v84, v85
	ds_write2_b32 v108, v57, v32 offset0:120 offset1:188
	s_waitcnt lgkmcnt(0)
	ds_read_b128 v[32:35], v88 offset:8448
	ds_read_b128 v[58:61], v88 offset:8512
	ds_read_b128 v[200:203], v88 offset:8576
	ds_read_b128 v[204:207], v88 offset:8640
	s_waitcnt lgkmcnt(3)
	v_mfma_f32_16x16x32_bf16 v[32:35], v[8:11], v[32:35], 0
	s_waitcnt lgkmcnt(2)
	v_mfma_f32_16x16x32_bf16 v[32:35], v[12:15], v[58:61], v[32:35]
	s_waitcnt lgkmcnt(1)
	v_mfma_f32_16x16x32_bf16 v[32:35], v[16:19], v[200:203], v[32:35]
	s_waitcnt lgkmcnt(0)
	v_mfma_f32_16x16x32_bf16 v[32:35], v[20:23], v[204:207], v[32:35]
	s_and_saveexec_b64 s[6:7], s[0:1]
	s_xor_b64 s[6:7], exec, s[6:7]
	s_cbranch_execz .LBB0_720
	v_sub_u32_e32 v47, 0x8ff, v56
	s_branch .LBB0_720
